# softmax-denominator reductions after the selected-block loop and in the output epilogue also moved from ds_bpermute to v_permlane16/32_swap
# speedup vs baseline: 1.0041x; 1.0041x over previous
.LBB0_422:
	s_or_b64 exec, exec, s[14:15]
	v_or_b32_e32 v134, v202, v190
	v_mov_b32_e32 v135, v203
	v_lshl_add_u64 v[142:143], v[204:205], 2, s[58:59]
	v_lshlrev_b64 v[134:135], 1, v[134:135]
	global_load_dword v132, v[142:143], off
	v_lshl_add_u64 v[134:135], s[62:63], 0, v[134:135]
	v_or_b32_e32 v136, v202, v192
	v_mov_b32_e32 v137, v203
	global_load_dwordx2 v[124:125], v[134:135], off
	v_lshlrev_b64 v[136:137], 1, v[136:137]
	v_or_b32_e32 v138, v202, v194
	v_mov_b32_e32 v139, v203
	v_lshl_add_u64 v[136:137], s[62:63], 0, v[136:137]
	v_lshlrev_b64 v[138:139], 1, v[138:139]
	global_load_dwordx2 v[126:127], v[136:137], off
	v_lshl_add_u64 v[138:139], s[62:63], 0, v[138:139]
	v_or_b32_e32 v140, v202, v196
	v_mov_b32_e32 v141, v203
	global_load_dwordx2 v[128:129], v[138:139], off
	v_lshlrev_b64 v[140:141], 1, v[140:141]
	v_lshl_add_u64 v[140:141], s[62:63], 0, v[140:141]
	global_load_dwordx2 v[130:131], v[140:141], off
	v_or_b32_e32 v30, v202, v190
	v_mov_b32_e32 v31, v203
	v_lshlrev_b64 v[30:31], 1, v[30:31]
	ds_read2st64_b32 v[2:3], v213 offset1:1
	ds_read2st64_b32 v[12:13], v213 offset0:2 offset1:3
	ds_read2st64_b32 v[14:15], v213 offset0:4 offset1:5
	ds_read2st64_b32 v[16:17], v213 offset0:6 offset1:7
	ds_read2st64_b32 v[18:19], v213 offset0:8 offset1:9
	ds_read2st64_b32 v[24:25], v213 offset0:10 offset1:11
	ds_read2st64_b32 v[26:27], v213 offset0:12 offset1:13
	ds_read2st64_b32 v[28:29], v213 offset0:14 offset1:15
	v_mov_b32_e32 v34, v234
	v_mov_b32_e32 v249, v234
	s_nop 1
	v_permlane16_swap_b32_e32 v34, v249
	v_mov_b32_e32 v35, v203
	v_lshl_add_u64 v[30:31], s[48:49], 0, v[30:31]
	v_add_u32_e32 v226, s55, v226
	v_add_u32_e32 v225, s77, v225
	s_waitcnt lgkmcnt(0)
	v_add_f32_e32 v36, v34, v249
	v_mov_b32_e32 v37, v36
	v_mov_b32_e32 v249, v36
	s_nop 1
	v_permlane32_swap_b32_e32 v37, v249
	v_or_b32_e32 v34, v202, v192
	v_lshlrev_b64 v[34:35], 1, v[34:35]
	s_waitcnt lgkmcnt(0)
	v_add_f32_e32 v38, v37, v249
	v_div_scale_f32 v39, s[0:1], v38, v38, 1.0
	v_rcp_f32_e32 v40, v39
	v_div_scale_f32 v41, vcc, 1.0, v38, 1.0
	v_fma_f32 v42, -v39, v40, 1.0
	v_fmac_f32_e32 v40, v42, v40
	v_mul_f32_e32 v42, v41, v40
	v_fma_f32 v43, -v39, v42, v41
	v_fmac_f32_e32 v42, v43, v40
	v_fma_f32 v39, -v39, v42, v41
	v_div_fmas_f32 v39, v39, v40, v42
	v_div_fixup_f32 v39, v39, v38, 1.0
	v_cmp_lt_f32_e32 vcc, 0, v38
	s_waitcnt vmcnt(0)
	v_mov_b32_e32 v1, v132
	v_mov_b64_e32 v[32:33], v[124:125]
	v_lshlrev_b32_e32 v40, 16, v32
	v_cndmask_b32_e32 v38, 0, v39, vcc
	v_mul_f32_e32 v38, v1, v38
	v_pk_fma_f32 v[2:3], v[38:39], v[44:45], v[2:3] op_sel_hi:[0,1,1]
	v_pk_fma_f32 v[12:13], v[38:39], v[46:47], v[12:13] op_sel_hi:[0,1,1]
	v_and_b32_e32 v41, 0xffff0000, v32
	v_lshlrev_b32_e32 v32, 16, v33
	v_and_b32_e32 v33, 0xffff0000, v33
	v_pk_mul_f32 v[2:3], v[2:3], v[40:41]
	v_pk_mul_f32 v[12:13], v[12:13], v[32:33]
	v_cvt_pk_bf16_f32 v2, v2, v3
	v_cvt_pk_bf16_f32 v3, v12, v13
	global_store_dwordx2 v[30:31], v[2:3], off
	v_pk_fma_f32 v[14:15], v[38:39], v[20:21], v[14:15] op_sel_hi:[0,1,1]
	v_pk_fma_f32 v[16:17], v[38:39], v[22:23], v[16:17] op_sel_hi:[0,1,1]
	v_or_b32_e32 v12, v202, v194
	v_mov_b32_e32 v13, v203
	v_lshlrev_b64 v[12:13], 1, v[12:13]
	v_lshl_add_u64 v[30:31], s[48:49], 0, v[34:35]
	v_pk_fma_f32 v[4:5], v[38:39], v[4:5], v[18:19] op_sel_hi:[0,1,1]
	v_pk_fma_f32 v[6:7], v[38:39], v[6:7], v[24:25] op_sel_hi:[0,1,1]
	v_or_b32_e32 v202, v202, v196
	v_lshl_add_u64 v[12:13], s[48:49], 0, v[12:13]
	v_cmp_lt_i32_e32 vcc, s91, v226
	s_or_b64 s[80:81], vcc, s[80:81]
	v_mov_b64_e32 v[2:3], v[126:127]
	v_lshlrev_b32_e32 v20, 16, v2
	v_and_b32_e32 v21, 0xffff0000, v2
	v_lshlrev_b32_e32 v2, 16, v3
	v_and_b32_e32 v3, 0xffff0000, v3
	v_pk_mul_f32 v[14:15], v[14:15], v[20:21]
	v_pk_mul_f32 v[2:3], v[16:17], v[2:3]
	v_cvt_pk_bf16_f32 v14, v14, v15
	v_cvt_pk_bf16_f32 v15, v2, v3
	global_store_dwordx2 v[30:31], v[14:15], off
	v_lshlrev_b64 v[14:15], 1, v[202:203]
	v_mov_b64_e32 v[2:3], v[128:129]
	v_lshlrev_b32_e32 v18, 16, v2
	v_and_b32_e32 v19, 0xffff0000, v2
	v_lshlrev_b32_e32 v2, 16, v3
	v_and_b32_e32 v3, 0xffff0000, v3
	v_pk_mul_f32 v[4:5], v[4:5], v[18:19]
	v_pk_mul_f32 v[2:3], v[6:7], v[2:3]
	v_cvt_pk_bf16_f32 v4, v4, v5
	v_cvt_pk_bf16_f32 v5, v2, v3
	global_store_dwordx2 v[12:13], v[4:5], off
	v_pk_fma_f32 v[6:7], v[38:39], v[8:9], v[26:27] op_sel_hi:[0,1,1]
	v_pk_fma_f32 v[8:9], v[38:39], v[10:11], v[28:29] op_sel_hi:[0,1,1]
	v_lshl_add_u64 v[4:5], s[48:49], 0, v[14:15]
	v_mov_b64_e32 v[2:3], v[130:131]
	v_lshlrev_b32_e32 v10, 16, v2
	v_and_b32_e32 v11, 0xffff0000, v2
	v_lshlrev_b32_e32 v2, 16, v3
	v_and_b32_e32 v3, 0xffff0000, v3
	v_pk_mul_f32 v[6:7], v[6:7], v[10:11]
	v_pk_mul_f32 v[2:3], v[8:9], v[2:3]
	v_cvt_pk_bf16_f32 v6, v6, v7
	v_cvt_pk_bf16_f32 v7, v2, v3
	global_store_dwordx2 v[4:5], v[6:7], off
	s_andn2_b64 exec, exec, s[80:81]
	s_cbranch_execz .LBB0_418

.LBB0_607:
	s_or_b64 exec, exec, s[16:17]
	v_lshl_add_u64 v[2:3], v[204:205], 2, s[52:53]
	global_load_dword v56, v[2:3], off
	global_load_dwordx4 v[12:15], v[148:149], off offset:64
	global_load_dwordx4 v[16:19], v[148:149], off
	v_mov_b32_e32 v4, v237
	v_mov_b32_e32 v249, v237
	s_nop 1
	v_permlane16_swap_b32_e32 v4, v249
	ds_read2st64_b32 v[8:9], v213 offset1:1
	ds_read2st64_b32 v[10:11], v213 offset0:2 offset1:3
	ds_read2st64_b32 v[54:55], v213 offset0:4 offset1:5
	ds_read_b32 v57, v213 offset:1536
	v_max_i32_e32 v5, 0x1ff, v227
	v_mov_b32_e32 v2, v0
	v_mov_b32_e32 v3, v0
	s_waitcnt lgkmcnt(4)
	v_add_f32_e32 v58, v4, v249
	v_mov_b32_e32 v59, v58
	v_mov_b32_e32 v249, v58
	s_nop 1
	v_permlane32_swap_b32_e32 v59, v249
	v_add_u32_e32 v48, 0xfffffe01, v5
	v_mov_b32_e32 v1, v0
	v_mov_b64_e32 v[46:47], v[2:3]
	v_mov_b64_e32 v[22:23], v[2:3]
	s_waitcnt lgkmcnt(0)
	v_add_f32_e32 v58, v59, v249
	v_div_scale_f32 v59, s[0:1], v58, v58, 1.0
	v_rcp_f32_e32 v60, v59
	v_div_scale_f32 v61, vcc, 1.0, v58, 1.0
	v_mov_b64_e32 v[6:7], v[2:3]
	v_fma_f32 v62, -v59, v60, 1.0
	v_fmac_f32_e32 v60, v62, v60
	v_mul_f32_e32 v62, v61, v60
	v_fma_f32 v63, -v59, v62, v61
	v_fmac_f32_e32 v62, v63, v60
	v_fma_f32 v59, -v59, v62, v61
	v_div_fmas_f32 v59, v59, v60, v62
	v_div_fixup_f32 v59, v59, v58, 1.0
	v_cmp_lt_f32_e32 vcc, 0, v58
	v_lshrrev_b32_e32 v48, 6, v48
	v_mov_b32_e32 v234, 0
	v_cndmask_b32_e32 v58, 0, v59, vcc
	v_mov_b64_e32 v[44:45], v[0:1]
	v_mov_b64_e32 v[20:21], v[0:1]
	v_mov_b64_e32 v[4:5], v[0:1]
	v_cmp_le_i32_e64 s[0:1], v48, v229
	s_waitcnt vmcnt(2)
	v_mul_f32_e32 v56, v56, v58
	v_fma_f32 v8, v56, v40, v8
	v_fmac_f32_e32 v9, v56, v41
	v_fma_f32 v10, v56, v42, v10
	v_fmac_f32_e32 v11, v56, v43
	v_fma_f32 v36, v56, v36, v54
	v_fmac_f32_e32 v55, v56, v37
	v_fmac_f32_e32 v57, v56, v38
	v_fmac_f32_e32 v49, v56, v39
	v_fmac_f32_e32 v52, v56, v32
	v_fmac_f32_e32 v53, v56, v33
	v_fmac_f32_e32 v26, v56, v34
	v_fmac_f32_e32 v27, v56, v35
	v_fmac_f32_e32 v50, v56, v28
	v_fmac_f32_e32 v51, v56, v29
	v_fmac_f32_e32 v24, v56, v30
	v_fmac_f32_e32 v25, v56, v31
	ds_write2st64_b32 v213, v8, v9 offset1:1
	ds_write2st64_b32 v213, v10, v11 offset0:2 offset1:3
	ds_write2st64_b32 v213, v36, v55 offset0:4 offset1:5
	ds_write2st64_b32 v213, v57, v49 offset0:6 offset1:7
	ds_write2st64_b32 v213, v52, v53 offset0:8 offset1:9
	ds_write2st64_b32 v213, v26, v27 offset0:10 offset1:11
	ds_write2st64_b32 v213, v50, v51 offset0:12 offset1:13
	ds_write2st64_b32 v213, v24, v25 offset0:14 offset1:15
	v_mov_b64_e32 v[10:11], v[2:3]
	v_mov_b64_e32 v[8:9], v[0:1]
	s_waitcnt vmcnt(0)
	s_and_saveexec_b64 s[14:15], s[0:1]
	s_cbranch_execz .LBB0_422
	v_mov_b32_e32 v2, v0
	v_mov_b32_e32 v3, v0
	v_mov_b32_e32 v1, v0
	v_mov_b64_e32 v[46:47], v[2:3]
	v_mov_b64_e32 v[22:23], v[2:3]
	v_mov_b64_e32 v[6:7], v[2:3]
	v_mov_b64_e32 v[10:11], v[2:3]
	v_mov_b64_e32 v[44:45], v[0:1]
	v_mov_b64_e32 v[20:21], v[0:1]
	v_mov_b64_e32 v[4:5], v[0:1]
	v_mov_b64_e32 v[8:9], v[0:1]
	v_add_u32_e32 v231, 0xfffffe04, v227
	v_add_u32_e32 v232, 0xfffffe01, v228
	v_mov_b32_e32 v235, 0xf149f2ca
	v_mov_b32_e32 v236, 0
	v_readfirstlane_b32 s32, v227
	v_readfirstlane_b32 s22, v48
	v_readfirstlane_b32 s24, v229
	v_readfirstlane_b32 s75, v191
	v_and_b32_e32 v60, 63, v191
	v_lshlrev_b32_e32 v60, 4, v60
	s_mov_b32 s95, 0
	s_lshl_b32 s75, s75, 4
	s_and_b32 s93, s32, 0xffffffe0
	s_max_i32 s12, s93, 0x1ff
	s_sub_i32 s12, s12, 0x1ff
	s_lshr_b32 s12, s12, 6
	s_add_i32 s13, s93, 31
	s_lshr_b32 s13, s13, 6
	v_readlane_b32 s36, v254, 0
	v_readlane_b32 s37, v254, 1
	v_readlane_b32 s72, v254, 2
	s_mov_b32 s94, s75
	s_add_i32 s98, s32, 0xfffffe04
	v_lshl_add_u64 v[64:65], v[186:187], 0, s[94:95]
	v_lshl_add_u64 v[66:67], v[188:189], 0, s[94:95]
	v_add_u32_e32 v237, s55, v226
	v_lshlrev_b32_e32 v237, 2, v237
	s_nop 0
	v_readfirstlane_b32 s101, v237
	s_and_b32 s93, s101, 0xffffffe0
	s_max_i32 s100, s93, 0x1ff
	s_sub_i32 s100, s100, 0x1ff
	s_lshr_b32 s100, s100, 6
	s_sub_i32 s100, s100, s13
	s_add_i32 s100, s100, -1
